# scan: static s_setprio 1 for waves 4-7 over the whole scan phase (reset to 0 at phase end), on top of the C/B L2 prefetch
# speedup vs baseline: 1.0035x; 1.0031x over previous
;     __device__ __forceinline__ const char* b(const pg8::Unit& u) const { return (const char*)ws + boff + (size_t)u.pn * 256 * K_ * 2 + (u.kq < 0 ? 0 : u.kq * (K_ / 4) * 2); }
;     __device__ __forceinline__ const char* b(const pg8::Unit& u) const { return (const char*)ws + boff + (size_t)u.pn * 256 * D * 2; }
;     __device__ __forceinline__ const char* b(const pg8::Unit& u) const { return (const char*)ws + boff + (size_t)u.pn * 256 * D * 2; }
;     __device__ __forceinline__ const char* b(const pg8::Unit& u) const { return (const char*)ws + WS_A + ((size_t)u.pn * 256 * D + (size_t)(u.pm >> 1) * 256) * 2; }
; template <int MODE> __device__ __forceinline__ void ssd_scan_phase(Frame& F, int j, bool ctx_out) {
;     ...
;     for (int item = blockIdx.x; item < 256; item += F.G) {
;         const int ph = item & 1, dir = (item >> 1) & 1, g = (item >> 2) & 7, b = item >> 5, h = g * 8 + w;
;         const float a_h = -expf(F.in[I_ALOG][(j * 2 + dir) * NH + h]) * LOG2E;
.LBB0_472:
	s_cmp_lt_u32 s33, 0x100
	s_cbranch_scc1 .Lscan_prio_skip
	s_setprio 1

; #define LAS __attribute__((address_space(3)))
; #define PHASE(id, k, ...) do { if (PHON(id) && IN(k)) { for (int rep_ = 0; rep_ < REPS(id); ++rep_) { __VA_ARGS__; if (rep_ + 1 < REPS(id)) xcd_barrier(bar, F.wave == 0 && fresh_lane() == 0); } SEAM(k); } } while (0)
; __global__ void __launch_bounds__(NWAVES * 64, 2) trunk_fwd(Args args) {
;     ...
;     LAS unsigned char* ring = F.lds;
;     ...
;         PHASE(2, pb + 6, norm_mod_phase(F, L, F.in[I_NFFN] + (size_t)L * D, 3, nrows_ffn, (const float*)(F.ws + WS_MOD) + (size_t)L * 9 * MODW + 2 * D, nullptr, L == 0 ? F.in[I_X] : nullptr, L == 0 ? F.in[I_CTX] : nullptr));
.LBB0_540:
	s_setprio 0
	s_mul_i32 s0, s82, 10
	s_add_i32 s6, s0, 6
	v_readlane_b32 s0, v251, 2
	v_readlane_b32 s1, v251, 3
	s_cmp_ge_i32 s6, s1
	s_cbranch_scc1 .LBB0_554
	v_readlane_b32 s0, v251, 34
	v_readlane_b32 s1, v251, 35
	s_andn2_b64 vcc, exec, s[0:1]
	s_mov_b64 s[4:5], 0
	v_readlane_b32 s27, v254, 6
	v_readlane_b32 s44, v254, 7
	s_cbranch_vccnz .LBB0_543
	v_mbcnt_lo_u32_b32 v0, -1, 0
	v_mbcnt_hi_u32_b32 v0, -1, v0
	s_nop 0
	v_cmp_eq_u32_e32 vcc, 0, v0
	s_and_b64 s[4:5], vcc, exec
